# diff-attention main loop: softmax VALU merged into QK/PV MFMA gaps, row sums under PV
# speedup vs baseline: 1.0095x; 1.0095x over previous
.LBB0_215:
	s_add_i32 s6, s5, 0x4000
	s_and_b32 s6, s6, 0xc000
	s_add_i32 s7, s15, s6
	v_lshl_add_u64 v[208:209], s[74:75], 0, v[206:207]
	s_add_i32 s6, s16, s6
	v_lshl_add_u64 v[68:69], v[208:209], 0, s[36:37]
	s_mov_b32 m0, s7
	v_lshl_add_u64 v[210:211], s[74:75], 0, v[80:81]
	s_waitcnt vmcnt(4)
	s_barrier
	global_load_lds_dwordx4 v[68:69], off
	v_lshl_add_u64 v[68:69], v[210:211], 0, s[58:59]
	s_mov_b32 m0, s6
	v_lshl_add_u64 v[212:213], s[74:75], 0, v[204:205]
	global_load_lds_dwordx4 v[68:69], off
	v_lshl_add_u64 v[68:69], v[212:213], 0, s[36:37]
	s_add_i32 m0, s7, 0x2000
	v_lshl_add_u64 v[214:215], s[74:75], 0, v[202:203]
	global_load_lds_dwordx4 v[68:69], off
	v_lshl_add_u64 v[68:69], v[214:215], 0, s[58:59]
	s_add_i32 m0, s6, 0x2000
	s_add_i32 s6, s5, 0xffff8000
	global_load_lds_dwordx4 v[68:69], off
	s_and_b32 s6, s6, 0x8000
	s_add_i32 s7, s6, 0
	v_add_u32_e32 v0, s7, v230
	ds_read_b128 v[68:71], v0 offset:16384
	ds_read_b128 v[72:75], v0 offset:24576
	v_add_u32_e32 v0, s7, v231
	ds_read_b128 v[76:79], v0 offset:16384
	ds_read_b128 v[162:165], v0 offset:24576
	v_max3_f32 v240, v98, v82, v99
	v_max3_f32 v66, v83, v100, v84
	s_waitcnt lgkmcnt(0)
	v_mfma_f32_32x32x16_bf16 v[146:161], v[68:71], v[190:193], v[114:129]
	v_add_u32_e32 v0, s7, v229
	v_max3_f32 v240, v240, v101, v85
	v_max3_f32 v66, v66, v102, v86
	v_mfma_f32_32x32x16_bf16 v[130:145], v[72:75], v[190:193], v[114:129]
	ds_read_b128 v[68:71], v0 offset:16384
	ds_read_b128 v[72:75], v0 offset:24576
	v_add_u32_e32 v0, s7, v233
	v_max3_f32 v240, v240, v103, v87
	v_max3_f32 v66, v66, v104, v88
	v_mfma_f32_32x32x16_bf16 v[146:161], v[76:79], v[186:189], v[146:161]
	ds_read_b128 v[76:79], v0 offset:16384
	ds_read_b128 v[166:169], v0 offset:24576
	v_max3_f32 v240, v240, v105, v89
	v_max3_f32 v66, v66, v106, v90
	v_mfma_f32_32x32x16_bf16 v[130:145], v[162:165], v[186:189], v[130:145]
	s_waitcnt lgkmcnt(0)
	v_max3_f32 v240, v240, v107, v91
	v_max3_f32 v66, v66, v108, v92
	v_mfma_f32_32x32x16_bf16 v[146:161], v[68:71], v[182:185], v[146:161]
	v_max3_f32 v240, v240, v109, v93
	v_max3_f32 v66, v66, v110, v94
	v_mfma_f32_32x32x16_bf16 v[130:145], v[72:75], v[182:185], v[130:145]
	v_max3_f32 v240, v240, v111, v95
	v_max3_f32 v66, v66, v112, v96
	v_mfma_f32_32x32x16_bf16 v[146:161], v[76:79], v[178:181], v[146:161]
	v_max3_f32 v240, v240, v113, v97
	v_max3_f32 v240, v240, v66, v66
	v_mfma_f32_32x32x16_bf16 v[130:145], v[166:169], v[178:181], v[130:145]
	s_add_i32 s7, s7, 0x10000
	v_add_u32_e32 v0, s7, v227
	ds_read_b128 v[194:197], v0
	ds_read_b128 v[76:79], v0 offset:4096
	ds_read_b128 v[72:75], v0 offset:8192
	ds_read_b128 v[68:71], v0 offset:12288
	v_mov_b32_e32 v66, v240
	s_nop 1
	v_permlane32_swap_b32_e32 v240, v66
	v_max3_f32 v198, v240, v66, v66
	s_nop 0
	v_pk_add_f32 v[162:163], v[200:201], v[198:199]
	s_nop 0
	v_cmp_gt_f32_e32 vcc, v162, v163
	s_nop 1
	v_cndmask_b32_e32 v0, v201, v162, vcc
	v_cmp_gt_f32_e32 vcc, v0, v201
	s_cbranch_vccz .LBB0_226
	v_sub_f32_e32 v66, v201, v0
	v_exp_f32_e32 v66, v66
	v_xor_b32_e32 v162, 0x80000000, v0
	v_mov_b32_e32 v163, v162
	v_mov_b32_e32 v164, v162
	v_pk_mul_f32 v[64:65], v[64:65], v[66:67] op_sel_hi:[1,0]
	v_pk_mul_f32 v[62:63], v[62:63], v[66:67] op_sel_hi:[1,0]
	v_pk_mul_f32 v[60:61], v[60:61], v[66:67] op_sel_hi:[1,0]
	v_pk_mul_f32 v[58:59], v[58:59], v[66:67] op_sel_hi:[1,0]
	v_pk_mul_f32 v[56:57], v[56:57], v[66:67] op_sel_hi:[1,0]
	v_pk_mul_f32 v[54:55], v[54:55], v[66:67] op_sel_hi:[1,0]
	v_pk_mul_f32 v[52:53], v[52:53], v[66:67] op_sel_hi:[1,0]
	v_pk_mul_f32 v[50:51], v[50:51], v[66:67] op_sel_hi:[1,0]
	v_pk_mul_f32 v[48:49], v[48:49], v[66:67] op_sel_hi:[1,0]
	v_pk_mul_f32 v[46:47], v[46:47], v[66:67] op_sel_hi:[1,0]
	v_pk_mul_f32 v[44:45], v[44:45], v[66:67] op_sel_hi:[1,0]
	v_pk_mul_f32 v[42:43], v[42:43], v[66:67] op_sel_hi:[1,0]
	v_pk_mul_f32 v[40:41], v[40:41], v[66:67] op_sel_hi:[1,0]
	v_pk_mul_f32 v[38:39], v[38:39], v[66:67] op_sel_hi:[1,0]
	v_pk_mul_f32 v[36:37], v[36:37], v[66:67] op_sel_hi:[1,0]
	v_pk_mul_f32 v[34:35], v[34:35], v[66:67] op_sel_hi:[1,0]
	v_pk_mul_f32 v[32:33], v[32:33], v[66:67] op_sel_hi:[1,0]
	v_pk_mul_f32 v[30:31], v[30:31], v[66:67] op_sel_hi:[1,0]
	v_pk_mul_f32 v[28:29], v[28:29], v[66:67] op_sel_hi:[1,0]
	v_pk_mul_f32 v[26:27], v[26:27], v[66:67] op_sel_hi:[1,0]
	v_pk_mul_f32 v[24:25], v[24:25], v[66:67] op_sel_hi:[1,0]
	v_pk_mul_f32 v[22:23], v[22:23], v[66:67] op_sel_hi:[1,0]
	v_pk_mul_f32 v[20:21], v[20:21], v[66:67] op_sel_hi:[1,0]
	v_pk_mul_f32 v[18:19], v[18:19], v[66:67] op_sel_hi:[1,0]
	v_pk_mul_f32 v[16:17], v[16:17], v[66:67] op_sel_hi:[1,0]
	v_pk_mul_f32 v[14:15], v[14:15], v[66:67] op_sel_hi:[1,0]
	v_pk_mul_f32 v[12:13], v[12:13], v[66:67] op_sel_hi:[1,0]
	v_pk_mul_f32 v[10:11], v[10:11], v[66:67] op_sel_hi:[1,0]
	v_pk_mul_f32 v[8:9], v[8:9], v[66:67] op_sel_hi:[1,0]
	v_pk_mul_f32 v[6:7], v[6:7], v[66:67] op_sel_hi:[1,0]
	v_pk_mul_f32 v[4:5], v[4:5], v[66:67] op_sel_hi:[1,0]
	v_pk_mul_f32 v[2:3], v[2:3], v[66:67] op_sel_hi:[1,0]
	v_mul_f32_e32 v232, v232, v66
	v_mov_b32_e32 v165, v162
	v_mov_b32_e32 v166, v162
	v_mov_b32_e32 v167, v162
	v_mov_b32_e32 v168, v162
	v_mov_b32_e32 v169, v162
	v_mov_b32_e32 v170, v162
	v_mov_b32_e32 v171, v162
	v_mov_b32_e32 v172, v162
	v_mov_b32_e32 v173, v162
	v_mov_b32_e32 v174, v162
	v_mov_b32_e32 v175, v162
	v_mov_b32_e32 v176, v162
	v_mov_b32_e32 v177, v162
	v_mov_b32_e32 v201, v0
	v_mov_b32_e32 v66, v162
	v_mov_b32_e32 v115, v162
	v_mov_b32_e32 v116, v162
	v_mov_b32_e32 v117, v162
	v_mov_b32_e32 v118, v162
	v_mov_b32_e32 v119, v162
	v_mov_b32_e32 v120, v162
	v_mov_b32_e32 v121, v162
	v_mov_b32_e32 v122, v162
	v_mov_b32_e32 v123, v162
	v_mov_b32_e32 v124, v162
	v_mov_b32_e32 v125, v162
	v_mov_b32_e32 v126, v162
	v_mov_b32_e32 v127, v162
	v_mov_b32_e32 v128, v162
	v_mov_b32_e32 v129, v162
	v_sub_f32_e32 v0, v0, v200
	v_cmp_neq_f32_e32 vcc, 0, v0
	s_cbranch_vccz .LBB0_218

; #define DA_WAIT_BAR(N) do { asm volatile("s_waitcnt vmcnt(" #N ")" ::: "memory"); __builtin_amdgcn_s_barrier(); } while (0)
; __device__ __forceinline__ void dattn_unit(LAS unsigned char* lds, const bf16_t* Qp, const bf16_t* Kp, const bf16_t* Vtp, int qb, bf16_t* Op, const float* lq1, const float* lk1, const float* lq2, const float* lk2, const float* subg, float outscale, int tid) {
;     ...
;         DA_WAIT_BAR(4); if (kt + 4 < nk) DA_DMA(kt + 4, kt & 3); DA_QK(sa, mra, (kt + 2) & 3); DA_SOFTMAX_PV(sb, mrb, (kt + 1) & 3, false, kt + 1);
.LBB0_218:
	v_exp_f32_e32 v198, v98
	v_exp_f32_e32 v0, v99
	v_exp_f32_e32 v200, v100
	v_exp_f32_e32 v98, v101
	v_exp_f32_e32 v238, v102
	v_exp_f32_e32 v99, v103
	v_exp_f32_e32 v239, v104
	v_exp_f32_e32 v100, v105
	v_cvt_pk_bf16_f32 v240, v198, v0
	v_cvt_pk_bf16_f32 v241, v200, v98
	v_cvt_pk_bf16_f32 v242, v238, v99
	v_cvt_pk_bf16_f32 v243, v239, v100
	v_exp_f32_e32 v105, v106
	s_waitcnt lgkmcnt(0)
	v_mfma_f32_32x32x16_bf16 v[50:65], v[194:197], v[240:243], v[50:65]
	v_add_u32_e32 v248, s7, v219
	v_exp_f32_e32 v101, v107
	v_exp_f32_e32 v106, v108
	v_exp_f32_e32 v102, v109
	v_mfma_f32_32x32x16_bf16 v[34:49], v[76:79], v[240:243], v[34:49]
	v_exp_f32_e32 v107, v110
	v_exp_f32_e32 v103, v111
	v_exp_f32_e32 v108, v112
	v_mfma_f32_32x32x16_bf16 v[18:33], v[72:75], v[240:243], v[18:33]
	ds_read_b128 v[72:75], v248
	ds_read_b128 v[76:79], v248 offset:4096
	ds_read_b128 v[194:197], v248 offset:8192
	ds_read_b128 v[220:223], v248 offset:12288
	v_exp_f32_e32 v104, v113
	v_cvt_pk_bf16_f32 v244, v105, v101
	v_cvt_pk_bf16_f32 v245, v106, v102
	v_mfma_f32_32x32x16_bf16 v[2:17], v[68:71], v[240:243], v[2:17]
	v_cvt_pk_bf16_f32 v246, v107, v103
	v_cvt_pk_bf16_f32 v247, v108, v104
	v_exp_f32_e32 v109, v82
	v_exp_f32_e32 v82, v83
	s_waitcnt lgkmcnt(0)
	v_mfma_f32_32x32x16_bf16 v[50:65], v[72:75], v[244:247], v[50:65]
	v_add_u32_e32 v248, s7, v218
	v_exp_f32_e32 v110, v84
	v_exp_f32_e32 v83, v85
	v_exp_f32_e32 v111, v86
	v_mfma_f32_32x32x16_bf16 v[34:49], v[76:79], v[244:247], v[34:49]
	v_exp_f32_e32 v84, v87
	v_exp_f32_e32 v112, v88
	v_exp_f32_e32 v85, v89
	v_mfma_f32_32x32x16_bf16 v[18:33], v[194:197], v[244:247], v[18:33]
	ds_read_b128 v[68:71], v248
	ds_read_b128 v[72:75], v248 offset:4096
	ds_read_b128 v[76:79], v248 offset:8192
	ds_read_b128 v[194:197], v248 offset:12288
	v_exp_f32_e32 v90, v90
	v_exp_f32_e32 v86, v91
	v_exp_f32_e32 v91, v92
	v_mfma_f32_32x32x16_bf16 v[2:17], v[220:223], v[244:247], v[2:17]
	v_exp_f32_e32 v87, v93
	v_exp_f32_e32 v92, v94
	v_exp_f32_e32 v88, v95
	v_exp_f32_e32 v93, v96
	v_exp_f32_e32 v89, v97
	v_cvt_pk_bf16_f32 v94, v109, v82
	v_cvt_pk_bf16_f32 v95, v110, v83
	v_cvt_pk_bf16_f32 v96, v111, v84
	v_cvt_pk_bf16_f32 v97, v112, v85
	v_add_f32_e32 v240, 0, v198
	v_add_f32_e32 v241, 0, v0
	s_waitcnt lgkmcnt(0)
	v_mfma_f32_32x32x16_bf16 v[50:65], v[68:71], v[94:97], v[50:65]
	v_add_u32_e32 v113, s7, v217
	v_cvt_pk_bf16_f32 v248, v90, v86
	v_cvt_pk_bf16_f32 v249, v91, v87
	v_add_f32_e32 v240, v200, v240
	v_add_f32_e32 v241, v98, v241
	v_add_f32_e32 v240, v238, v240
	v_mfma_f32_32x32x16_bf16 v[34:49], v[72:75], v[94:97], v[34:49]
	v_cvt_pk_bf16_f32 v250, v92, v88
	v_cvt_pk_bf16_f32 v251, v93, v89
	v_add_f32_e32 v241, v99, v241
	v_add_f32_e32 v240, v239, v240
	v_add_f32_e32 v241, v100, v241
	v_mfma_f32_32x32x16_bf16 v[18:33], v[76:79], v[94:97], v[18:33]
	ds_read_b128 v[68:71], v113
	ds_read_b128 v[72:75], v113 offset:4096
	ds_read_b128 v[76:79], v113 offset:8192
	ds_read_b128 v[220:223], v113 offset:12288
	v_add_f32_e32 v240, v105, v240
	v_add_f32_e32 v241, v101, v241
	v_add_f32_e32 v240, v106, v240
	v_add_f32_e32 v241, v102, v241
	v_mfma_f32_32x32x16_bf16 v[2:17], v[194:197], v[94:97], v[2:17]
	v_add_f32_e32 v240, v107, v240
	v_add_f32_e32 v241, v103, v241
	v_add_f32_e32 v240, v108, v240
	v_add_f32_e32 v241, v104, v241
	v_add_f32_e32 v240, v109, v240
	v_add_f32_e32 v241, v82, v241
	s_waitcnt lgkmcnt(0)
	v_mfma_f32_32x32x16_bf16 v[50:65], v[68:71], v[248:251], v[50:65]
	v_add_f32_e32 v240, v110, v240
	v_add_f32_e32 v241, v83, v241
	v_add_f32_e32 v240, v111, v240
	v_add_f32_e32 v241, v84, v241
	v_add_f32_e32 v240, v112, v240
	v_add_f32_e32 v241, v85, v241
	v_mfma_f32_32x32x16_bf16 v[34:49], v[72:75], v[248:251], v[34:49]
	v_add_f32_e32 v240, v90, v240
	v_add_f32_e32 v241, v86, v241
	v_add_f32_e32 v240, v91, v240
	v_add_f32_e32 v241, v87, v241
	v_add_f32_e32 v240, v92, v240
	v_add_f32_e32 v241, v88, v241
	v_mfma_f32_32x32x16_bf16 v[18:33], v[76:79], v[248:251], v[18:33]
	v_add_f32_e32 v240, v93, v240
	v_add_f32_e32 v241, v89, v241
	v_add_f32_e32 v0, v241, v240
	v_add_f32_e32 v0, v232, v0
	v_mfma_f32_32x32x16_bf16 v[2:17], v[220:223], v[248:251], v[2:17]
	s_waitcnt vmcnt(4)
	s_add_i32 s17, s4, 4
	s_cmp_gt_u32 s17, s11
	s_barrier
	s_cbranch_scc1 .LBB0_220
	s_add_i32 s17, s15, s6
	s_add_i32 s7, s7, s14
	v_lshl_add_u64 v[68:69], v[208:209], 0, s[22:23]
	s_mov_b32 m0, s17
	s_mov_b64 s[34:35], 0x20400200
	global_load_lds_dwordx4 v[68:69], off
	v_lshl_add_u64 v[68:69], v[210:211], 0, s[34:35]
	s_mov_b32 m0, s7
	s_nop 0
	global_load_lds_dwordx4 v[68:69], off
	v_lshl_add_u64 v[68:69], v[212:213], 0, s[22:23]
	s_add_i32 m0, s17, 0x2000
	s_nop 0
	global_load_lds_dwordx4 v[68:69], off
	v_lshl_add_u64 v[68:69], v[214:215], 0, s[34:35]
	s_add_i32 m0, s7, 0x2000
	s_nop 0
	global_load_lds_dwordx4 v[68:69], off
.LBB0_220:
	s_bitset1_b32 s6, 14
	s_and_b32 s7, s5, 0x8000
	s_add_i32 s7, s7, 0
	v_add_u32_e32 v72, s7, v230
	v_add_u32_e32 v82, s7, v231
	ds_read_b128 v[68:71], v72
	ds_read_b128 v[72:75], v72 offset:8192
	ds_read_b128 v[76:79], v82
	ds_read_b128 v[194:197], v82 offset:8192
	s_waitcnt lgkmcnt(0)
	v_mfma_f32_32x32x16_bf16 v[98:113], v[68:71], v[190:193], v[162:177]
	v_mfma_f32_32x32x16_bf16 v[82:97], v[72:75], v[190:193], v[162:177]
	v_add_u32_e32 v72, s7, v229
	ds_read_b128 v[68:71], v72
	ds_read_b128 v[72:75], v72 offset:8192
	s_nop 3
	v_add_u32_e32 v163, s7, v233
	v_mfma_f32_32x32x16_bf16 v[98:113], v[76:79], v[186:189], v[98:113]
	ds_read_b128 v[76:79], v163
	ds_read_b128 v[164:167], v163 offset:8192
	v_max3_f32 v163, v146, v130, v147
	v_max3_f32 v168, v131, v148, v132
	v_mfma_f32_32x32x16_bf16 v[82:97], v[194:197], v[186:189], v[82:97]
	s_waitcnt lgkmcnt(0)
	v_max3_f32 v163, v163, v149, v133
	v_max3_f32 v168, v168, v150, v134
	v_mfma_f32_32x32x16_bf16 v[98:113], v[68:71], v[182:185], v[98:113]
	v_max3_f32 v163, v163, v151, v135
	v_max3_f32 v168, v168, v152, v136
	v_mfma_f32_32x32x16_bf16 v[82:97], v[72:75], v[182:185], v[82:97]
	v_max3_f32 v163, v163, v153, v137
	v_max3_f32 v168, v168, v154, v138
	v_max3_f32 v163, v163, v155, v139
	v_max3_f32 v168, v168, v156, v140
	v_mfma_f32_32x32x16_bf16 v[98:113], v[76:79], v[178:181], v[98:113]
	v_max3_f32 v163, v163, v157, v141
	v_max3_f32 v168, v168, v158, v142
	v_max3_f32 v163, v163, v159, v143
	v_max3_f32 v168, v168, v160, v144
	v_mfma_f32_32x32x16_bf16 v[82:97], v[164:167], v[178:181], v[82:97]
	v_add_u32_e32 v68, s6, v234
	ds_read_b128 v[164:167], v68
	ds_read_b128 v[76:79], v68 offset:4096
	ds_read_b128 v[72:75], v68 offset:8192
	ds_read_b128 v[68:71], v68 offset:12288
	v_max3_f32 v163, v163, v161, v145
	v_max3_f32 v163, v163, v168, v168
	v_mov_b32_e32 v168, v163
	s_nop 1
	v_permlane32_swap_b32_e32 v163, v168
	v_max3_f32 v163, v163, v168, v168
	v_add_f32_e32 v168, 0x41000000, v201
	v_sub_f32_e32 v163, v163, v114
	v_cmp_gt_f32_e32 vcc, v163, v168
	s_nop 1
	v_cndmask_b32_e32 v163, v201, v163, vcc
	v_cmp_gt_f32_e32 vcc, v163, v201
	s_cbranch_vccz .LBB0_222
	v_sub_f32_e32 v66, v201, v163
	v_exp_f32_e32 v116, v66
	v_xor_b32_e32 v66, 0x80000000, v163
	v_mov_b32_e32 v201, v163
	v_mov_b32_e32 v115, v66
	v_pk_mul_f32 v[64:65], v[64:65], v[116:117] op_sel_hi:[1,0]
	v_pk_mul_f32 v[62:63], v[62:63], v[116:117] op_sel_hi:[1,0]
	v_pk_mul_f32 v[60:61], v[60:61], v[116:117] op_sel_hi:[1,0]
	v_pk_mul_f32 v[58:59], v[58:59], v[116:117] op_sel_hi:[1,0]
	v_pk_mul_f32 v[56:57], v[56:57], v[116:117] op_sel_hi:[1,0]
	v_pk_mul_f32 v[54:55], v[54:55], v[116:117] op_sel_hi:[1,0]
	v_pk_mul_f32 v[52:53], v[52:53], v[116:117] op_sel_hi:[1,0]
	v_pk_mul_f32 v[50:51], v[50:51], v[116:117] op_sel_hi:[1,0]
	v_pk_mul_f32 v[48:49], v[48:49], v[116:117] op_sel_hi:[1,0]
	v_pk_mul_f32 v[46:47], v[46:47], v[116:117] op_sel_hi:[1,0]
	v_pk_mul_f32 v[44:45], v[44:45], v[116:117] op_sel_hi:[1,0]
	v_pk_mul_f32 v[42:43], v[42:43], v[116:117] op_sel_hi:[1,0]
	v_pk_mul_f32 v[40:41], v[40:41], v[116:117] op_sel_hi:[1,0]
	v_pk_mul_f32 v[38:39], v[38:39], v[116:117] op_sel_hi:[1,0]
	v_pk_mul_f32 v[36:37], v[36:37], v[116:117] op_sel_hi:[1,0]
	v_pk_mul_f32 v[34:35], v[34:35], v[116:117] op_sel_hi:[1,0]
	v_pk_mul_f32 v[32:33], v[32:33], v[116:117] op_sel_hi:[1,0]
	v_pk_mul_f32 v[30:31], v[30:31], v[116:117] op_sel_hi:[1,0]
	v_pk_mul_f32 v[28:29], v[28:29], v[116:117] op_sel_hi:[1,0]
	v_pk_mul_f32 v[26:27], v[26:27], v[116:117] op_sel_hi:[1,0]
	v_pk_mul_f32 v[24:25], v[24:25], v[116:117] op_sel_hi:[1,0]
	v_pk_mul_f32 v[22:23], v[22:23], v[116:117] op_sel_hi:[1,0]
	v_pk_mul_f32 v[20:21], v[20:21], v[116:117] op_sel_hi:[1,0]
	v_pk_mul_f32 v[18:19], v[18:19], v[116:117] op_sel_hi:[1,0]
	v_pk_mul_f32 v[16:17], v[16:17], v[116:117] op_sel_hi:[1,0]
	v_pk_mul_f32 v[14:15], v[14:15], v[116:117] op_sel_hi:[1,0]
	v_pk_mul_f32 v[12:13], v[12:13], v[116:117] op_sel_hi:[1,0]
	v_pk_mul_f32 v[10:11], v[10:11], v[116:117] op_sel_hi:[1,0]
	v_pk_mul_f32 v[8:9], v[8:9], v[116:117] op_sel_hi:[1,0]
	v_pk_mul_f32 v[6:7], v[6:7], v[116:117] op_sel_hi:[1,0]
	v_pk_mul_f32 v[4:5], v[4:5], v[116:117] op_sel_hi:[1,0]
	v_pk_mul_f32 v[2:3], v[2:3], v[116:117] op_sel_hi:[1,0]
	v_mul_f32_e32 v0, v0, v116
	v_mov_b32_e32 v116, v66
	v_mov_b32_e32 v117, v66
	v_mov_b32_e32 v118, v66
	v_mov_b32_e32 v119, v66
	v_mov_b32_e32 v120, v66
	v_mov_b32_e32 v121, v66
	v_mov_b32_e32 v122, v66
	v_mov_b32_e32 v123, v66
	v_mov_b32_e32 v124, v66
	v_mov_b32_e32 v125, v66
	v_mov_b32_e32 v126, v66
	v_mov_b32_e32 v127, v66
	v_mov_b32_e32 v128, v66
	v_mov_b32_e32 v129, v66

; #define DA_WAIT_BAR(N) do { asm volatile("s_waitcnt vmcnt(" #N ")" ::: "memory"); __builtin_amdgcn_s_barrier(); } while (0)
; __device__ __forceinline__ void dattn_unit(LAS unsigned char* lds, const bf16_t* Qp, const bf16_t* Kp, const bf16_t* Vtp, int qb, bf16_t* Op, const float* lq1, const float* lk1, const float* lq2, const float* lk2, const float* subg, float outscale, int tid) {
;     ...
;     for (int kt = 0; kt < nfull; kt += 2) {
;         DA_WAIT_BAR(4); DA_DMA(kt + 3, (kt + 3) & 3); DA_QK(sb, mrb, (kt + 1) & 3); DA_SOFTMAX_PV(sa, mra, kt & 3, false, kt);
;         DA_WAIT_BAR(4); if (kt + 4 < nk) DA_DMA(kt + 4, kt & 3); DA_QK(sa, mra, (kt + 2) & 3); DA_SOFTMAX_PV(sb, mrb, (kt + 1) & 3, false, kt + 1);
;     }
.LBB0_224:
	v_exp_f32_e32 v168, v146
	v_exp_f32_e32 v169, v147
	v_exp_f32_e32 v170, v148
	v_exp_f32_e32 v171, v149
	v_exp_f32_e32 v172, v150
	v_exp_f32_e32 v173, v151
	v_exp_f32_e32 v174, v152
	v_exp_f32_e32 v175, v153
	v_cvt_pk_bf16_f32 v146, v168, v169
	v_cvt_pk_bf16_f32 v147, v170, v171
	v_cvt_pk_bf16_f32 v148, v172, v173
	v_cvt_pk_bf16_f32 v149, v174, v175
	v_exp_f32_e32 v154, v154
	s_waitcnt lgkmcnt(0)
	v_mfma_f32_32x32x16_bf16 v[50:65], v[164:167], v[146:149], v[50:65]
	v_add_u32_e32 v248, s6, v235
	v_exp_f32_e32 v155, v155
	v_pk_add_f32 v[168:169], v[168:169], 0 op_sel_hi:[1,0]
	v_exp_f32_e32 v156, v156
	v_mfma_f32_32x32x16_bf16 v[34:49], v[76:79], v[146:149], v[34:49]
	v_exp_f32_e32 v157, v157
	v_pk_add_f32 v[168:169], v[170:171], v[168:169]
	v_exp_f32_e32 v158, v158
	v_mfma_f32_32x32x16_bf16 v[18:33], v[72:75], v[146:149], v[18:33]
	ds_read_b128 v[72:75], v248
	ds_read_b128 v[76:79], v248 offset:4096
	ds_read_b128 v[240:243], v248 offset:8192
	ds_read_b128 v[244:247], v248 offset:12288
	v_exp_f32_e32 v159, v159
	v_pk_add_f32 v[168:169], v[172:173], v[168:169]
	v_exp_f32_e32 v160, v160
	v_mfma_f32_32x32x16_bf16 v[2:17], v[68:71], v[146:149], v[2:17]
	v_exp_f32_e32 v161, v161
	v_pk_add_f32 v[168:169], v[174:175], v[168:169]
	v_cvt_pk_bf16_f32 v150, v154, v155
	v_cvt_pk_bf16_f32 v151, v156, v157
	v_cvt_pk_bf16_f32 v152, v158, v159
	v_cvt_pk_bf16_f32 v153, v160, v161
	v_exp_f32_e32 v170, v130
	s_waitcnt lgkmcnt(0)
	v_mfma_f32_32x32x16_bf16 v[50:65], v[72:75], v[150:153], v[50:65]
	v_exp_f32_e32 v171, v131
	v_pk_add_f32 v[154:155], v[154:155], v[168:169]
	v_exp_f32_e32 v172, v132
	v_mfma_f32_32x32x16_bf16 v[34:49], v[76:79], v[150:153], v[34:49]
	v_exp_f32_e32 v173, v133
	v_pk_add_f32 v[154:155], v[156:157], v[154:155]
	v_exp_f32_e32 v174, v134
	v_mfma_f32_32x32x16_bf16 v[18:33], v[240:243], v[150:153], v[18:33]
	v_add_u32_e32 v248, s6, v236
	ds_read_b128 v[68:71], v248
	ds_read_b128 v[72:75], v248 offset:4096
	ds_read_b128 v[76:79], v248 offset:8192
	ds_read_b128 v[240:243], v248 offset:12288
	v_exp_f32_e32 v175, v135
	v_pk_add_f32 v[154:155], v[158:159], v[154:155]
	v_exp_f32_e32 v176, v136
	v_mfma_f32_32x32x16_bf16 v[2:17], v[244:247], v[150:153], v[2:17]
	v_exp_f32_e32 v177, v137
	v_pk_add_f32 v[154:155], v[160:161], v[154:155]
	v_cvt_pk_bf16_f32 v130, v170, v171
	v_cvt_pk_bf16_f32 v131, v172, v173
	v_cvt_pk_bf16_f32 v132, v174, v175
	v_cvt_pk_bf16_f32 v133, v176, v177
	v_exp_f32_e32 v138, v138
	s_waitcnt lgkmcnt(0)
	v_mfma_f32_32x32x16_bf16 v[50:65], v[68:71], v[130:133], v[50:65]
	v_add_u32_e32 v248, s6, v237
	v_exp_f32_e32 v139, v139
	v_pk_add_f32 v[154:155], v[170:171], v[154:155]
	v_exp_f32_e32 v140, v140
	v_mfma_f32_32x32x16_bf16 v[34:49], v[72:75], v[130:133], v[34:49]
	v_exp_f32_e32 v141, v141
	v_pk_add_f32 v[154:155], v[172:173], v[154:155]
	v_exp_f32_e32 v142, v142
	v_mfma_f32_32x32x16_bf16 v[18:33], v[76:79], v[130:133], v[18:33]
	ds_read_b128 v[68:71], v248
	ds_read_b128 v[72:75], v248 offset:4096
	ds_read_b128 v[76:79], v248 offset:8192
	ds_read_b128 v[244:247], v248 offset:12288
	v_exp_f32_e32 v143, v143
	v_pk_add_f32 v[154:155], v[174:175], v[154:155]
	v_exp_f32_e32 v144, v144
	v_mfma_f32_32x32x16_bf16 v[2:17], v[240:243], v[130:133], v[2:17]
	v_exp_f32_e32 v145, v145
	v_pk_add_f32 v[154:155], v[176:177], v[154:155]
	v_cvt_pk_bf16_f32 v134, v138, v139
	v_pk_add_f32 v[138:139], v[138:139], v[154:155]
	s_add_i32 s4, s4, 2
	v_pk_add_f32 v[138:139], v[140:141], v[138:139]
	v_pk_add_f32 v[138:139], v[142:143], v[138:139]
	v_pk_add_f32 v[138:139], v[144:145], v[138:139]
	v_cvt_pk_bf16_f32 v135, v140, v141
	v_cvt_pk_bf16_f32 v136, v142, v143
	v_cvt_pk_bf16_f32 v137, v144, v145
	v_add_f32_e32 v114, v138, v139
	s_waitcnt lgkmcnt(0)
	v_mfma_f32_32x32x16_bf16 v[50:65], v[68:71], v[134:137], v[50:65]
	v_add_f32_e32 v232, v0, v114
	v_mfma_f32_32x32x16_bf16 v[34:49], v[72:75], v[134:137], v[34:49]
	v_mfma_f32_32x32x16_bf16 v[18:33], v[76:79], v[134:137], v[18:33]
	v_mfma_f32_32x32x16_bf16 v[2:17], v[244:247], v[134:137], v[2:17]
	s_add_i32 s5, s5, 0x8000
	v_xor_b32_e32 v200, 0x80000000, v162
	v_lshl_add_u64 v[80:81], v[80:81], 0, s[96:97]
	v_lshl_add_u64 v[202:203], v[202:203], 0, s[96:97]
	v_lshl_add_u64 v[204:205], v[204:205], 0, s[18:19]
	s_cmp_ge_u32 s4, s11
	v_lshl_add_u64 v[206:207], v[206:207], 0, s[18:19]
	s_cbranch_scc1 .LBB0_228
	v_mov_b32_e32 v114, v66
	s_branch .LBB0_215

;     __device__ __forceinline__ void operator()(const Acc& acc, const Unit& u, int wr, int wc, int fr, int fq) const {
;     ...
; #pragma unroll
;         for (int bj = 0; bj < 2; ++bj)
; #pragma unroll
;             for (int n = 0; n < 2; ++n) {
;                 f32x4 gv = {1.f, 1.f, 1.f, 1.f}, bv = {0.f, 0.f, 0.f, 0.f};
;                 if (stats) { gv = *(const f32x4*)(g + colb + bj * 128 + 4 * n); bv = *(const f32x4*)(b + colb + bj * 128 + 4 * n); }
; #pragma unroll
;                 for (int ai = 0; ai < 2; ++ai)
; #pragma unroll
;                     for (int m = 0; m < 4; ++m) { const size_t off = (size_t)(u.pm * 256 + ai * 128 + wr * 64 + m * 16 + fr) * DM + colb + bj * 128 + 4 * n;
;                         f32x4 xv = *(const f32x4*)(xprev + off);
;                         if (stats) xv = ((xv - st[ai][m].x) * st[ai][m].y) * gv + bv;
;                         *(f32x4*)(out + off) = xv * ALPHA + acc[ai][bj][m][n]; }
;             }
.LBB0_887:
	v_lshlrev_b64 v[190:191], 13, v[190:191]
	v_lshl_add_u64 v[190:191], s[72:73], 0, v[190:191]
	v_lshl_add_u64 v[190:191], v[190:191], 0, v[88:89]
	global_load_dwordx4 v[212:215], v[190:191], off
	v_lshlrev_b64 v[84:85], 13, v[84:85]
	v_lshl_add_u64 v[84:85], s[72:73], 0, v[84:85]
	s_and_b64 vcc, exec, s[42:43]
	v_mov_b32_e32 v83, 1.0
	v_mov_b32_e32 v87, 0
	s_waitcnt vmcnt(0)
	v_sub_f32_e32 v217, v215, v184
	v_sub_f32_e32 v216, v214, v184
	v_sub_f32_e32 v219, v213, v184
	v_sub_f32_e32 v218, v212, v184
	v_pk_mul_f32 v[218:219], v[186:187], v[218:219] op_sel_hi:[0,1]
	v_pk_mul_f32 v[216:217], v[186:187], v[216:217] op_sel_hi:[0,1]
	v_pk_fma_f32 v[216:217], v[128:129], v[216:217], v[132:133]
	v_pk_fma_f32 v[218:219], v[126:127], v[218:219], v[130:131]
	v_cndmask_b32_e64 v215, v217, v215, s[38:39]
	v_cndmask_b32_e64 v213, v219, v213, s[38:39]
	v_cndmask_b32_e64 v212, v218, v212, s[38:39]
	v_cndmask_b32_e64 v214, v216, v214, s[38:39]
	v_pk_fma_f32 v[144:145], v[214:215], s[24:25], v[144:145] op_sel_hi:[1,0,1]
	v_pk_fma_f32 v[142:143], v[212:213], s[24:25], v[142:143] op_sel_hi:[1,0,1]
	global_store_dwordx4 v[190:191], v[142:145], off
	s_nop 1
	v_lshlrev_b64 v[142:143], 13, v[206:207]
	v_lshl_add_u64 v[142:143], s[72:73], 0, v[142:143]
	v_lshl_add_u64 v[142:143], v[142:143], 0, v[88:89]
	global_load_dwordx4 v[212:215], v[142:143], off
	s_waitcnt vmcnt(0)
	v_sub_f32_e32 v145, v215, v180
	v_sub_f32_e32 v144, v214, v180
	v_sub_f32_e32 v207, v213, v180
	v_sub_f32_e32 v206, v212, v180
	v_pk_mul_f32 v[206:207], v[182:183], v[206:207] op_sel_hi:[0,1]
	v_pk_mul_f32 v[144:145], v[182:183], v[144:145] op_sel_hi:[0,1]
	v_pk_fma_f32 v[144:145], v[128:129], v[144:145], v[132:133]
	v_pk_fma_f32 v[206:207], v[126:127], v[206:207], v[130:131]
	v_cndmask_b32_e64 v145, v145, v215, s[38:39]
	v_cndmask_b32_e64 v207, v207, v213, s[38:39]
	v_cndmask_b32_e64 v206, v206, v212, s[38:39]
	v_cndmask_b32_e64 v144, v144, v214, s[38:39]
	v_pk_fma_f32 v[140:141], v[144:145], s[24:25], v[140:141] op_sel_hi:[1,0,1]
	v_pk_fma_f32 v[138:139], v[206:207], s[24:25], v[138:139] op_sel_hi:[1,0,1]
	global_store_dwordx4 v[142:143], v[138:141], off
	s_nop 1
	v_lshlrev_b64 v[138:139], 13, v[204:205]
	v_lshl_add_u64 v[138:139], s[72:73], 0, v[138:139]
	v_lshl_add_u64 v[138:139], v[138:139], 0, v[88:89]
	global_load_dwordx4 v[204:207], v[138:139], off
	s_waitcnt vmcnt(0)
	v_sub_f32_e32 v141, v207, v176
	v_sub_f32_e32 v140, v206, v176
	v_sub_f32_e32 v145, v205, v176
	v_sub_f32_e32 v144, v204, v176
	v_pk_mul_f32 v[144:145], v[178:179], v[144:145] op_sel_hi:[0,1]
	v_pk_mul_f32 v[140:141], v[178:179], v[140:141] op_sel_hi:[0,1]
	v_pk_fma_f32 v[140:141], v[128:129], v[140:141], v[132:133]
	v_pk_fma_f32 v[144:145], v[126:127], v[144:145], v[130:131]
	v_cndmask_b32_e64 v141, v141, v207, s[38:39]
	v_cndmask_b32_e64 v145, v145, v205, s[38:39]
	v_cndmask_b32_e64 v144, v144, v204, s[38:39]
	v_cndmask_b32_e64 v140, v140, v206, s[38:39]
	v_pk_fma_f32 v[136:137], v[140:141], s[24:25], v[136:137] op_sel_hi:[1,0,1]
	v_pk_fma_f32 v[134:135], v[144:145], s[24:25], v[134:135] op_sel_hi:[1,0,1]
	global_store_dwordx4 v[138:139], v[134:137], off
	s_nop 1
	v_lshlrev_b64 v[134:135], 13, v[202:203]
	v_lshl_add_u64 v[134:135], s[72:73], 0, v[134:135]
	v_lshl_add_u64 v[134:135], v[134:135], 0, v[88:89]
	global_load_dwordx4 v[202:205], v[134:135], off
	s_waitcnt vmcnt(0)
	v_sub_f32_e32 v137, v205, v172
	v_sub_f32_e32 v136, v204, v172
	v_sub_f32_e32 v141, v203, v172
	v_sub_f32_e32 v140, v202, v172
	v_pk_mul_f32 v[140:141], v[174:175], v[140:141] op_sel_hi:[0,1]
	v_pk_mul_f32 v[136:137], v[174:175], v[136:137] op_sel_hi:[0,1]
	v_pk_fma_f32 v[136:137], v[128:129], v[136:137], v[132:133]
	v_pk_fma_f32 v[140:141], v[126:127], v[140:141], v[130:131]
	v_cndmask_b32_e64 v137, v137, v205, s[38:39]
	v_cndmask_b32_e64 v141, v141, v203, s[38:39]
	v_cndmask_b32_e64 v140, v140, v202, s[38:39]
	v_cndmask_b32_e64 v136, v136, v204, s[38:39]
	v_pk_fma_f32 v[124:125], v[136:137], s[24:25], v[124:125] op_sel_hi:[1,0,1]
	v_pk_fma_f32 v[122:123], v[140:141], s[24:25], v[122:123] op_sel_hi:[1,0,1]
	global_store_dwordx4 v[134:135], v[122:125], off
	s_nop 1
	v_lshlrev_b64 v[122:123], 13, v[200:201]
	v_lshl_add_u64 v[122:123], s[72:73], 0, v[122:123]
	v_lshl_add_u64 v[122:123], v[122:123], 0, v[88:89]
	global_load_dwordx4 v[200:203], v[122:123], off
	s_waitcnt vmcnt(0)
	v_sub_f32_e32 v125, v203, v168
	v_sub_f32_e32 v124, v202, v168
	v_sub_f32_e32 v137, v201, v168
	v_sub_f32_e32 v136, v200, v168
	v_pk_mul_f32 v[136:137], v[170:171], v[136:137] op_sel_hi:[0,1]
	v_pk_mul_f32 v[124:125], v[170:171], v[124:125] op_sel_hi:[0,1]
	v_pk_fma_f32 v[124:125], v[128:129], v[124:125], v[132:133]
	v_pk_fma_f32 v[136:137], v[126:127], v[136:137], v[130:131]
	v_cndmask_b32_e64 v125, v125, v203, s[38:39]
	v_cndmask_b32_e64 v137, v137, v201, s[38:39]
	v_cndmask_b32_e64 v136, v136, v200, s[38:39]
	v_cndmask_b32_e64 v124, v124, v202, s[38:39]
	v_pk_fma_f32 v[120:121], v[124:125], s[24:25], v[120:121] op_sel_hi:[1,0,1]
	v_pk_fma_f32 v[118:119], v[136:137], s[24:25], v[118:119] op_sel_hi:[1,0,1]
	global_store_dwordx4 v[122:123], v[118:121], off
	s_nop 1
	v_lshlrev_b64 v[118:119], 13, v[196:197]
	v_lshl_add_u64 v[118:119], s[72:73], 0, v[118:119]
	v_lshl_add_u64 v[118:119], v[118:119], 0, v[88:89]
	global_load_dwordx4 v[200:203], v[118:119], off
	s_waitcnt vmcnt(0)
;     __device__ __forceinline__ void operator()(const Acc& acc, const Unit& u, int wr, int wc, int fr, int fq) const {
;     ...
; #pragma unroll
;         for (int bj = 0; bj < 2; ++bj)
; #pragma unroll
;             for (int n = 0; n < 2; ++n) {
;                 f32x4 gv = {1.f, 1.f, 1.f, 1.f}, bv = {0.f, 0.f, 0.f, 0.f};
;                 if (stats) { gv = *(const f32x4*)(g + colb + bj * 128 + 4 * n); bv = *(const f32x4*)(b + colb + bj * 128 + 4 * n); }
; #pragma unroll
;                 for (int ai = 0; ai < 2; ++ai)
; #pragma unroll
;                     for (int m = 0; m < 4; ++m) { const size_t off = (size_t)(u.pm * 256 + ai * 128 + wr * 64 + m * 16 + fr) * DM + colb + bj * 128 + 4 * n;
;                         f32x4 xv = *(const f32x4*)(xprev + off);
;                         if (stats) xv = ((xv - st[ai][m].x) * st[ai][m].y) * gv + bv;
;                         *(f32x4*)(out + off) = xv * ALPHA + acc[ai][bj][m][n]; }
;             }
	v_sub_f32_e32 v121, v203, v164
	v_sub_f32_e32 v120, v202, v164
	v_sub_f32_e32 v125, v201, v164
	v_sub_f32_e32 v124, v200, v164
	v_pk_mul_f32 v[124:125], v[166:167], v[124:125] op_sel_hi:[0,1]
	v_pk_mul_f32 v[120:121], v[166:167], v[120:121] op_sel_hi:[0,1]
	v_pk_fma_f32 v[120:121], v[128:129], v[120:121], v[132:133]
	v_pk_fma_f32 v[124:125], v[126:127], v[124:125], v[130:131]
	v_cndmask_b32_e64 v121, v121, v203, s[38:39]
	v_cndmask_b32_e64 v125, v125, v201, s[38:39]
	v_cndmask_b32_e64 v124, v124, v200, s[38:39]
	v_cndmask_b32_e64 v120, v120, v202, s[38:39]
	v_pk_fma_f32 v[116:117], v[120:121], s[24:25], v[116:117] op_sel_hi:[1,0,1]
	v_pk_fma_f32 v[114:115], v[124:125], s[24:25], v[114:115] op_sel_hi:[1,0,1]
	global_store_dwordx4 v[118:119], v[114:117], off
	s_nop 1
	v_lshlrev_b64 v[114:115], 13, v[194:195]
	v_lshl_add_u64 v[114:115], s[72:73], 0, v[114:115]
	v_lshl_add_u64 v[116:117], v[114:115], 0, v[88:89]
	global_load_dwordx4 v[194:197], v[116:117], off
	s_waitcnt vmcnt(0)
	v_sub_f32_e32 v115, v197, v160
	v_sub_f32_e32 v114, v196, v160
	v_sub_f32_e32 v121, v195, v160
	v_sub_f32_e32 v120, v194, v160
	v_pk_mul_f32 v[120:121], v[162:163], v[120:121] op_sel_hi:[0,1]
	v_pk_mul_f32 v[114:115], v[162:163], v[114:115] op_sel_hi:[0,1]
	v_pk_fma_f32 v[114:115], v[128:129], v[114:115], v[132:133]
	v_pk_fma_f32 v[120:121], v[126:127], v[120:121], v[130:131]
	v_cndmask_b32_e64 v115, v115, v197, s[38:39]
	v_cndmask_b32_e64 v121, v121, v195, s[38:39]
	v_cndmask_b32_e64 v120, v120, v194, s[38:39]
	v_cndmask_b32_e64 v114, v114, v196, s[38:39]
	v_pk_fma_f32 v[112:113], v[114:115], s[24:25], v[112:113] op_sel_hi:[1,0,1]
	v_pk_fma_f32 v[110:111], v[120:121], s[24:25], v[110:111] op_sel_hi:[1,0,1]
	v_lshl_add_u64 v[114:115], v[84:85], 0, v[88:89]
	global_store_dwordx4 v[116:117], v[110:113], off
	global_load_dwordx4 v[110:113], v[114:115], off
	s_waitcnt vmcnt(0)
	v_sub_f32_e32 v85, v113, v156
	v_sub_f32_e32 v84, v112, v156
	v_sub_f32_e32 v89, v111, v156
	v_sub_f32_e32 v88, v110, v156
	v_pk_mul_f32 v[88:89], v[158:159], v[88:89] op_sel_hi:[0,1]
	v_pk_mul_f32 v[84:85], v[158:159], v[84:85] op_sel_hi:[0,1]
	v_pk_fma_f32 v[84:85], v[128:129], v[84:85], v[132:133]
	v_pk_fma_f32 v[88:89], v[126:127], v[88:89], v[130:131]
	v_cndmask_b32_e64 v85, v85, v113, s[38:39]
	v_cndmask_b32_e64 v89, v89, v111, s[38:39]
	v_cndmask_b32_e64 v88, v88, v110, s[38:39]
	v_cndmask_b32_e64 v84, v84, v112, s[38:39]
	v_pk_fma_f32 v[108:109], v[84:85], s[24:25], v[108:109] op_sel_hi:[1,0,1]
	v_pk_fma_f32 v[106:107], v[88:89], s[24:25], v[106:107] op_sel_hi:[1,0,1]
	v_mov_b32_e32 v84, 1.0
	v_mov_b32_e32 v85, 1.0
	v_mov_b32_e32 v88, 0
	v_mov_b32_e32 v89, 0
	global_store_dwordx4 v[114:115], v[106:109], off
	s_cbranch_vccnz .LBB0_889
	global_load_dwordx4 v[82:85], v[192:193], off offset:16
	global_load_dwordx4 v[86:89], v[188:189], off offset:16
.LBB0_889:
	global_load_dwordx4 v[108:111], v[190:191], off offset:16
	v_mov_b32_e32 v187, v186
	v_mov_b32_e32 v183, v182
	v_mov_b32_e32 v179, v178
	v_mov_b32_e32 v175, v174
	v_mov_b32_e32 v171, v170
	v_mov_b32_e32 v167, v166
	v_mov_b32_e32 v163, v162
	v_mov_b32_e32 v159, v158
	s_and_b64 vcc, exec, s[42:43]
	s_waitcnt vmcnt(0)
	v_sub_f32_e32 v107, v109, v184
	v_sub_f32_e32 v106, v108, v184
	v_sub_f32_e32 v113, v111, v184
	v_sub_f32_e32 v112, v110, v184
	v_pk_mul_f32 v[120:121], v[186:187], v[106:107]
	v_mov_b32_e32 v106, v186
	v_mov_b32_e32 v107, v186
	v_pk_mul_f32 v[112:113], v[106:107], v[112:113]
	v_pk_fma_f32 v[120:121], v[82:83], v[120:121], v[86:87]
	v_pk_fma_f32 v[112:113], v[84:85], v[112:113], v[88:89]
	v_cndmask_b32_e64 v109, v121, v109, s[38:39]
	v_cndmask_b32_e64 v108, v120, v108, s[38:39]
	v_cndmask_b32_e64 v111, v113, v111, s[38:39]
	v_cndmask_b32_e64 v110, v112, v110, s[38:39]
	v_pk_fma_f32 v[104:105], v[110:111], s[24:25], v[104:105] op_sel_hi:[1,0,1]
	v_pk_fma_f32 v[102:103], v[108:109], s[24:25], v[102:103] op_sel_hi:[1,0,1]
	global_load_dwordx4 v[108:111], v[142:143], off offset:16
	s_nop 0
	global_store_dwordx4 v[190:191], v[102:105], off offset:16
	s_waitcnt vmcnt(1)
	s_nop 0
	v_sub_f32_e32 v103, v109, v180
	v_sub_f32_e32 v102, v108, v180
	v_sub_f32_e32 v105, v111, v180
	v_sub_f32_e32 v104, v110, v180
	v_pk_mul_f32 v[112:113], v[182:183], v[102:103]
	v_mov_b32_e32 v102, v182
	v_mov_b32_e32 v103, v182
	v_pk_mul_f32 v[104:105], v[102:103], v[104:105]
	v_pk_fma_f32 v[112:113], v[82:83], v[112:113], v[86:87]
	v_pk_fma_f32 v[104:105], v[84:85], v[104:105], v[88:89]
	v_cndmask_b32_e64 v109, v113, v109, s[38:39]
	v_cndmask_b32_e64 v108, v112, v108, s[38:39]
	v_cndmask_b32_e64 v105, v105, v111, s[38:39]
	v_cndmask_b32_e64 v104, v104, v110, s[38:39]
	v_pk_fma_f32 v[98:99], v[108:109], s[24:25], v[98:99] op_sel_hi:[1,0,1]
	global_load_dwordx4 v[108:111], v[138:139], off offset:16
	v_pk_fma_f32 v[100:101], v[104:105], s[24:25], v[100:101] op_sel_hi:[1,0,1]
	global_store_dwordx4 v[142:143], v[98:101], off offset:16
	s_waitcnt vmcnt(1)
	s_nop 0
	v_sub_f32_e32 v99, v109, v176
	v_sub_f32_e32 v98, v108, v176
	v_sub_f32_e32 v101, v111, v176
	v_sub_f32_e32 v100, v110, v176
	v_pk_mul_f32 v[104:105], v[178:179], v[98:99]
	v_mov_b32_e32 v98, v178
	v_mov_b32_e32 v99, v178
	v_pk_mul_f32 v[100:101], v[98:99], v[100:101]
	v_pk_fma_f32 v[104:105], v[82:83], v[104:105], v[86:87]
	v_pk_fma_f32 v[100:101], v[84:85], v[100:101], v[88:89]
	v_cndmask_b32_e64 v105, v105, v109, s[38:39]
	v_cndmask_b32_e64 v104, v104, v108, s[38:39]
	v_cndmask_b32_e64 v101, v101, v111, s[38:39]
	v_cndmask_b32_e64 v100, v100, v110, s[38:39]
	global_load_dwordx4 v[108:111], v[134:135], off offset:16
	v_pk_fma_f32 v[96:97], v[100:101], s[24:25], v[96:97] op_sel_hi:[1,0,1]
	v_pk_fma_f32 v[94:95], v[104:105], s[24:25], v[94:95] op_sel_hi:[1,0,1]
	global_store_dwordx4 v[138:139], v[94:97], off offset:16
	s_waitcnt vmcnt(1)
;     __device__ __forceinline__ void operator()(const Acc& acc, const Unit& u, int wr, int wc, int fr, int fq) const {
;     ...
; #pragma unroll
;         for (int bj = 0; bj < 2; ++bj)
; #pragma unroll
;             for (int n = 0; n < 2; ++n) {
;                 f32x4 gv = {1.f, 1.f, 1.f, 1.f}, bv = {0.f, 0.f, 0.f, 0.f};
;                 if (stats) { gv = *(const f32x4*)(g + colb + bj * 128 + 4 * n); bv = *(const f32x4*)(b + colb + bj * 128 + 4 * n); }
; #pragma unroll
;                 for (int ai = 0; ai < 2; ++ai)
; #pragma unroll
;                     for (int m = 0; m < 4; ++m) { const size_t off = (size_t)(u.pm * 256 + ai * 128 + wr * 64 + m * 16 + fr) * DM + colb + bj * 128 + 4 * n;
;                         f32x4 xv = *(const f32x4*)(xprev + off);
;                         if (stats) xv = ((xv - st[ai][m].x) * st[ai][m].y) * gv + bv;
;                         *(f32x4*)(out + off) = xv * ALPHA + acc[ai][bj][m][n]; }
;             }
	s_nop 0
	v_sub_f32_e32 v95, v109, v172
	v_sub_f32_e32 v94, v108, v172
	v_sub_f32_e32 v97, v111, v172
	v_sub_f32_e32 v96, v110, v172
	v_pk_mul_f32 v[100:101], v[174:175], v[94:95]
	v_mov_b32_e32 v94, v174
	v_mov_b32_e32 v95, v174
	v_pk_mul_f32 v[96:97], v[94:95], v[96:97]
	v_pk_fma_f32 v[100:101], v[82:83], v[100:101], v[86:87]
	v_pk_fma_f32 v[96:97], v[84:85], v[96:97], v[88:89]
	v_cndmask_b32_e64 v101, v101, v109, s[38:39]
	v_cndmask_b32_e64 v100, v100, v108, s[38:39]
	v_cndmask_b32_e64 v97, v97, v111, s[38:39]
	v_cndmask_b32_e64 v96, v96, v110, s[38:39]
	global_load_dwordx4 v[108:111], v[122:123], off offset:16
	v_pk_fma_f32 v[92:93], v[96:97], s[24:25], v[92:93] op_sel_hi:[1,0,1]
	v_pk_fma_f32 v[90:91], v[100:101], s[24:25], v[90:91] op_sel_hi:[1,0,1]
	global_store_dwordx4 v[134:135], v[90:93], off offset:16
	s_waitcnt vmcnt(1)
	s_nop 0
	v_sub_f32_e32 v91, v109, v168
	v_sub_f32_e32 v90, v108, v168
	v_sub_f32_e32 v93, v111, v168
	v_sub_f32_e32 v92, v110, v168
	v_pk_mul_f32 v[96:97], v[170:171], v[90:91]
	v_mov_b32_e32 v90, v170
	v_mov_b32_e32 v91, v170
	v_pk_mul_f32 v[92:93], v[90:91], v[92:93]
	v_pk_fma_f32 v[96:97], v[82:83], v[96:97], v[86:87]
	v_pk_fma_f32 v[92:93], v[84:85], v[92:93], v[88:89]
	v_cndmask_b32_e64 v97, v97, v109, s[38:39]
	v_cndmask_b32_e64 v96, v96, v108, s[38:39]
	v_cndmask_b32_e64 v93, v93, v111, s[38:39]
	v_cndmask_b32_e64 v92, v92, v110, s[38:39]
	global_load_dwordx4 v[108:111], v[118:119], off offset:16
	v_pk_fma_f32 v[80:81], v[92:93], s[24:25], v[80:81] op_sel_hi:[1,0,1]
	v_pk_fma_f32 v[78:79], v[96:97], s[24:25], v[78:79] op_sel_hi:[1,0,1]
	global_store_dwordx4 v[122:123], v[78:81], off offset:16
	s_waitcnt vmcnt(1)
	s_nop 0
	v_sub_f32_e32 v81, v109, v164
	v_sub_f32_e32 v80, v108, v164
	v_sub_f32_e32 v79, v111, v164
	v_sub_f32_e32 v78, v110, v164
	v_pk_mul_f32 v[92:93], v[166:167], v[80:81]
	v_mov_b32_e32 v80, v166
	v_mov_b32_e32 v81, v166
	v_pk_mul_f32 v[78:79], v[80:81], v[78:79]
	v_pk_fma_f32 v[92:93], v[82:83], v[92:93], v[86:87]
	v_pk_fma_f32 v[78:79], v[84:85], v[78:79], v[88:89]
	v_cndmask_b32_e64 v93, v93, v109, s[38:39]
	v_cndmask_b32_e64 v92, v92, v108, s[38:39]
	v_cndmask_b32_e64 v79, v79, v111, s[38:39]
	v_cndmask_b32_e64 v78, v78, v110, s[38:39]
	v_pk_fma_f32 v[76:77], v[78:79], s[24:25], v[76:77] op_sel_hi:[1,0,1]
	v_pk_fma_f32 v[74:75], v[92:93], s[24:25], v[74:75] op_sel_hi:[1,0,1]
	global_store_dwordx4 v[118:119], v[74:77], off offset:16
	global_load_dwordx4 v[74:77], v[116:117], off offset:16
	s_waitcnt vmcnt(0)
	v_sub_f32_e32 v93, v75, v160
	v_sub_f32_e32 v92, v74, v160
	v_sub_f32_e32 v79, v77, v160
	v_sub_f32_e32 v78, v76, v160
	v_pk_mul_f32 v[96:97], v[162:163], v[92:93]
	v_mov_b32_e32 v92, v162
	v_mov_b32_e32 v93, v162
	v_pk_mul_f32 v[78:79], v[92:93], v[78:79]
	v_pk_fma_f32 v[96:97], v[82:83], v[96:97], v[86:87]
	v_pk_fma_f32 v[78:79], v[84:85], v[78:79], v[88:89]
	v_cndmask_b32_e64 v75, v97, v75, s[38:39]
	v_cndmask_b32_e64 v74, v96, v74, s[38:39]
	v_cndmask_b32_e64 v77, v79, v77, s[38:39]
	v_cndmask_b32_e64 v76, v78, v76, s[38:39]
	v_pk_fma_f32 v[72:73], v[76:77], s[24:25], v[72:73] op_sel_hi:[1,0,1]
	v_pk_fma_f32 v[70:71], v[74:75], s[24:25], v[70:71] op_sel_hi:[1,0,1]
	global_store_dwordx4 v[116:117], v[70:73], off offset:16
	global_load_dwordx4 v[70:73], v[114:115], off offset:16
	v_mov_b32_e32 v96, v158
	v_mov_b32_e32 v97, v158
	v_mov_b32_e32 v78, 0
	v_mov_b32_e32 v79, 0
	s_waitcnt vmcnt(0)
	v_sub_f32_e32 v75, v73, v156
	v_sub_f32_e32 v74, v72, v156
	v_sub_f32_e32 v77, v71, v156
	v_sub_f32_e32 v76, v70, v156
	v_pk_mul_f32 v[76:77], v[158:159], v[76:77]
	v_pk_mul_f32 v[74:75], v[96:97], v[74:75]
	v_pk_fma_f32 v[76:77], v[82:83], v[76:77], v[86:87]
	v_pk_fma_f32 v[74:75], v[84:85], v[74:75], v[88:89]
	v_cndmask_b32_e64 v71, v77, v71, s[38:39]
	v_cndmask_b32_e64 v70, v76, v70, s[38:39]
	v_cndmask_b32_e64 v73, v75, v73, s[38:39]
	v_cndmask_b32_e64 v72, v74, v72, s[38:39]
	v_pk_fma_f32 v[64:65], v[72:73], s[24:25], v[64:65] op_sel_hi:[1,0,1]
	v_pk_fma_f32 v[62:63], v[70:71], s[24:25], v[62:63] op_sel_hi:[1,0,1]
	global_store_dwordx4 v[114:115], v[62:65], off offset:16
	v_mov_b32_e32 v70, 0
	v_mov_b32_e32 v72, 1.0
	v_mov_b32_e32 v62, 1.0
	v_mov_b32_e32 v73, 1.0
	v_mov_b32_e32 v74, 1.0
	v_mov_b32_e32 v75, 1.0
	v_mov_b32_e32 v76, 0
	v_mov_b32_e32 v77, 0
	s_cbranch_vccnz .LBB0_891
	global_load_dwordx4 v[72:75], v[192:193], off offset:512
	global_load_dwordx4 v[76:79], v[188:189], off offset:512
;     __device__ __forceinline__ void operator()(const Acc& acc, const Unit& u, int wr, int wc, int fr, int fq) const {
;     ...
; #pragma unroll
;         for (int bj = 0; bj < 2; ++bj)
; #pragma unroll
;             for (int n = 0; n < 2; ++n) {
;                 f32x4 gv = {1.f, 1.f, 1.f, 1.f}, bv = {0.f, 0.f, 0.f, 0.f};
;                 if (stats) { gv = *(const f32x4*)(g + colb + bj * 128 + 4 * n); bv = *(const f32x4*)(b + colb + bj * 128 + 4 * n); }
; #pragma unroll
;                 for (int ai = 0; ai < 2; ++ai)
; #pragma unroll
;                     for (int m = 0; m < 4; ++m) { const size_t off = (size_t)(u.pm * 256 + ai * 128 + wr * 64 + m * 16 + fr) * DM + colb + bj * 128 + 4 * n;
;                         f32x4 xv = *(const f32x4*)(xprev + off);
;                         if (stats) xv = ((xv - st[ai][m].x) * st[ai][m].y) * gv + bv;
;                         *(f32x4*)(out + off) = xv * ALPHA + acc[ai][bj][m][n]; }
;             }
.LBB0_891:
	global_load_dwordx4 v[82:85], v[190:191], off offset:512
	s_and_b64 vcc, exec, s[42:43]
	v_mov_b32_e32 v63, 1.0
	v_mov_b32_e32 v71, 0
	s_waitcnt vmcnt(0)
	v_sub_f32_e32 v65, v85, v184
	v_sub_f32_e32 v64, v84, v184
	v_sub_f32_e32 v87, v83, v184
	v_sub_f32_e32 v86, v82, v184
	v_pk_mul_f32 v[86:87], v[186:187], v[86:87]
	v_pk_mul_f32 v[64:65], v[106:107], v[64:65]
	v_pk_fma_f32 v[86:87], v[72:73], v[86:87], v[76:77]
	v_pk_fma_f32 v[64:65], v[74:75], v[64:65], v[78:79]
	v_cndmask_b32_e64 v83, v87, v83, s[38:39]
	v_cndmask_b32_e64 v82, v86, v82, s[38:39]
	v_cndmask_b32_e64 v65, v65, v85, s[38:39]
	v_cndmask_b32_e64 v64, v64, v84, s[38:39]
	v_pk_fma_f32 v[68:69], v[64:65], s[24:25], v[68:69] op_sel_hi:[1,0,1]
	v_pk_fma_f32 v[66:67], v[82:83], s[24:25], v[66:67] op_sel_hi:[1,0,1]
	global_store_dwordx4 v[190:191], v[66:69], off offset:512
	global_load_dwordx4 v[64:67], v[142:143], off offset:512
	s_waitcnt vmcnt(0)
	v_sub_f32_e32 v83, v65, v180
	v_sub_f32_e32 v69, v67, v180
	v_sub_f32_e32 v68, v66, v180
	v_sub_f32_e32 v82, v64, v180
	v_pk_mul_f32 v[82:83], v[182:183], v[82:83]
	v_pk_mul_f32 v[68:69], v[102:103], v[68:69]
	v_pk_fma_f32 v[82:83], v[72:73], v[82:83], v[76:77]
	v_pk_fma_f32 v[68:69], v[74:75], v[68:69], v[78:79]
	v_cndmask_b32_e64 v65, v83, v65, s[38:39]
	v_cndmask_b32_e64 v64, v82, v64, s[38:39]
	v_cndmask_b32_e64 v67, v69, v67, s[38:39]
	v_cndmask_b32_e64 v66, v68, v66, s[38:39]
	v_pk_fma_f32 v[60:61], v[66:67], s[24:25], v[60:61] op_sel_hi:[1,0,1]
	v_pk_fma_f32 v[58:59], v[64:65], s[24:25], v[58:59] op_sel_hi:[1,0,1]
	global_store_dwordx4 v[142:143], v[58:61], off offset:512
	global_load_dwordx4 v[58:61], v[138:139], off offset:512
	s_waitcnt vmcnt(0)
	v_sub_f32_e32 v65, v61, v176
	v_sub_f32_e32 v64, v60, v176
	v_sub_f32_e32 v67, v59, v176
	v_sub_f32_e32 v66, v58, v176
	v_pk_mul_f32 v[66:67], v[178:179], v[66:67]
	v_pk_mul_f32 v[64:65], v[98:99], v[64:65]
	v_pk_fma_f32 v[66:67], v[72:73], v[66:67], v[76:77]
	v_pk_fma_f32 v[64:65], v[74:75], v[64:65], v[78:79]
	v_cndmask_b32_e64 v59, v67, v59, s[38:39]
	v_cndmask_b32_e64 v58, v66, v58, s[38:39]
	v_cndmask_b32_e64 v61, v65, v61, s[38:39]
	v_cndmask_b32_e64 v60, v64, v60, s[38:39]
	v_pk_fma_f32 v[56:57], v[60:61], s[24:25], v[56:57] op_sel_hi:[1,0,1]
	v_pk_fma_f32 v[54:55], v[58:59], s[24:25], v[54:55] op_sel_hi:[1,0,1]
	global_store_dwordx4 v[138:139], v[54:57], off offset:512
	global_load_dwordx4 v[54:57], v[134:135], off offset:512
	v_mov_b32_e32 v64, 1.0
	v_mov_b32_e32 v65, 1.0
	s_waitcnt vmcnt(0)
	v_sub_f32_e32 v59, v57, v172
	v_sub_f32_e32 v58, v56, v172
	v_sub_f32_e32 v61, v55, v172
	v_sub_f32_e32 v60, v54, v172
	v_pk_mul_f32 v[60:61], v[174:175], v[60:61]
	v_pk_mul_f32 v[58:59], v[94:95], v[58:59]
	v_pk_fma_f32 v[60:61], v[72:73], v[60:61], v[76:77]
	v_pk_fma_f32 v[58:59], v[74:75], v[58:59], v[78:79]
	v_cndmask_b32_e64 v55, v61, v55, s[38:39]
	v_cndmask_b32_e64 v54, v60, v54, s[38:39]
	v_cndmask_b32_e64 v57, v59, v57, s[38:39]
	v_cndmask_b32_e64 v56, v58, v56, s[38:39]
	v_pk_fma_f32 v[52:53], v[56:57], s[24:25], v[52:53] op_sel_hi:[1,0,1]
	v_pk_fma_f32 v[50:51], v[54:55], s[24:25], v[50:51] op_sel_hi:[1,0,1]
	global_store_dwordx4 v[134:135], v[50:53], off offset:512
	global_load_dwordx4 v[50:53], v[122:123], off offset:512
	s_waitcnt vmcnt(0)
	v_sub_f32_e32 v55, v53, v168
	v_sub_f32_e32 v54, v52, v168
	v_sub_f32_e32 v57, v51, v168
	v_sub_f32_e32 v56, v50, v168
	v_pk_mul_f32 v[56:57], v[170:171], v[56:57]
	v_pk_mul_f32 v[54:55], v[90:91], v[54:55]
	v_pk_fma_f32 v[56:57], v[72:73], v[56:57], v[76:77]
	v_pk_fma_f32 v[54:55], v[74:75], v[54:55], v[78:79]
	v_cndmask_b32_e64 v51, v57, v51, s[38:39]
	v_cndmask_b32_e64 v50, v56, v50, s[38:39]
	v_cndmask_b32_e64 v53, v55, v53, s[38:39]
	v_cndmask_b32_e64 v52, v54, v52, s[38:39]
	v_pk_fma_f32 v[48:49], v[52:53], s[24:25], v[48:49] op_sel_hi:[1,0,1]
	v_pk_fma_f32 v[46:47], v[50:51], s[24:25], v[46:47] op_sel_hi:[1,0,1]
	global_store_dwordx4 v[122:123], v[46:49], off offset:512
	global_load_dwordx4 v[46:49], v[118:119], off offset:512
	s_waitcnt vmcnt(0)
	v_sub_f32_e32 v51, v49, v164
	v_sub_f32_e32 v50, v48, v164
	v_sub_f32_e32 v53, v47, v164
	v_sub_f32_e32 v52, v46, v164
	v_pk_mul_f32 v[52:53], v[166:167], v[52:53]
	v_pk_mul_f32 v[50:51], v[80:81], v[50:51]
	v_pk_fma_f32 v[52:53], v[72:73], v[52:53], v[76:77]
	v_pk_fma_f32 v[50:51], v[74:75], v[50:51], v[78:79]
	v_cndmask_b32_e64 v47, v53, v47, s[38:39]
	v_cndmask_b32_e64 v46, v52, v46, s[38:39]
	v_cndmask_b32_e64 v49, v51, v49, s[38:39]
	v_cndmask_b32_e64 v48, v50, v48, s[38:39]
	v_pk_fma_f32 v[44:45], v[48:49], s[24:25], v[44:45] op_sel_hi:[1,0,1]
	v_pk_fma_f32 v[42:43], v[46:47], s[24:25], v[42:43] op_sel_hi:[1,0,1]
	global_store_dwordx4 v[118:119], v[42:45], off offset:512
	global_load_dwordx4 v[42:45], v[116:117], off offset:512
	s_waitcnt vmcnt(0)
	v_sub_f32_e32 v47, v45, v160
	v_sub_f32_e32 v46, v44, v160
	v_sub_f32_e32 v49, v43, v160
	v_sub_f32_e32 v48, v42, v160
	v_pk_mul_f32 v[48:49], v[162:163], v[48:49]
	v_pk_mul_f32 v[46:47], v[92:93], v[46:47]
	v_pk_fma_f32 v[48:49], v[72:73], v[48:49], v[76:77]
	v_pk_fma_f32 v[46:47], v[74:75], v[46:47], v[78:79]
	v_cndmask_b32_e64 v43, v49, v43, s[38:39]
	v_cndmask_b32_e64 v42, v48, v42, s[38:39]
	v_cndmask_b32_e64 v45, v47, v45, s[38:39]
	v_cndmask_b32_e64 v44, v46, v44, s[38:39]
	v_pk_fma_f32 v[40:41], v[44:45], s[24:25], v[40:41] op_sel_hi:[1,0,1]
	v_pk_fma_f32 v[38:39], v[42:43], s[24:25], v[38:39] op_sel_hi:[1,0,1]
	global_store_dwordx4 v[116:117], v[38:41], off offset:512
	global_load_dwordx4 v[38:41], v[114:115], off offset:512
	s_waitcnt vmcnt(0)
	v_sub_f32_e32 v43, v41, v156
	v_sub_f32_e32 v42, v40, v156
	v_sub_f32_e32 v45, v39, v156
	v_sub_f32_e32 v44, v38, v156
	v_pk_mul_f32 v[44:45], v[158:159], v[44:45]
	v_pk_mul_f32 v[42:43], v[96:97], v[42:43]
	v_pk_fma_f32 v[44:45], v[72:73], v[44:45], v[76:77]
	v_pk_fma_f32 v[42:43], v[74:75], v[42:43], v[78:79]
	v_cndmask_b32_e64 v39, v45, v39, s[38:39]
	v_cndmask_b32_e64 v38, v44, v38, s[38:39]
	v_cndmask_b32_e64 v41, v43, v41, s[38:39]
	v_cndmask_b32_e64 v40, v42, v40, s[38:39]
	v_pk_fma_f32 v[32:33], v[40:41], s[24:25], v[32:33] op_sel_hi:[1,0,1]
	v_pk_fma_f32 v[30:31], v[38:39], s[24:25], v[30:31] op_sel_hi:[1,0,1]
	v_mov_b32_e32 v72, 0
	v_mov_b32_e32 v73, 0
	global_store_dwordx4 v[114:115], v[30:33], off offset:512
	s_cbranch_vccnz .LBB0_893
	global_load_dwordx4 v[62:65], v[192:193], off offset:528
	global_load_dwordx4 v[70:73], v[188:189], off offset:528
;     __device__ __forceinline__ void operator()(const Acc& acc, const Unit& u, int wr, int wc, int fr, int fq) const {
;     ...
; #pragma unroll
;         for (int bj = 0; bj < 2; ++bj)
; #pragma unroll
;             for (int n = 0; n < 2; ++n) {
;                 f32x4 gv = {1.f, 1.f, 1.f, 1.f}, bv = {0.f, 0.f, 0.f, 0.f};
;                 if (stats) { gv = *(const f32x4*)(g + colb + bj * 128 + 4 * n); bv = *(const f32x4*)(b + colb + bj * 128 + 4 * n); }
; #pragma unroll
;                 for (int ai = 0; ai < 2; ++ai)
; #pragma unroll
;                     for (int m = 0; m < 4; ++m) { const size_t off = (size_t)(u.pm * 256 + ai * 128 + wr * 64 + m * 16 + fr) * DM + colb + bj * 128 + 4 * n;
;                         f32x4 xv = *(const f32x4*)(xprev + off);
;                         if (stats) xv = ((xv - st[ai][m].x) * st[ai][m].y) * gv + bv;
;                         *(f32x4*)(out + off) = xv * ALPHA + acc[ai][bj][m][n]; }
;             }
.LBB0_893:
	global_load_dwordx4 v[30:33], v[190:191], off offset:528
	s_mov_b64 s[2:3], -1
	s_and_b64 vcc, exec, s[40:41]
	s_waitcnt vmcnt(0)
	v_sub_f32_e32 v41, v31, v184
	v_sub_f32_e32 v40, v30, v184
	v_sub_f32_e32 v39, v33, v184
	v_sub_f32_e32 v38, v32, v184
	v_pk_mul_f32 v[40:41], v[186:187], v[40:41]
	v_mov_b32_e32 v187, v186
	v_pk_mul_f32 v[38:39], v[186:187], v[38:39]
	v_pk_fma_f32 v[40:41], v[62:63], v[40:41], v[70:71]
	v_pk_fma_f32 v[38:39], v[64:65], v[38:39], v[72:73]
	v_cndmask_b32_e64 v31, v41, v31, s[38:39]
	v_cndmask_b32_e64 v30, v40, v30, s[38:39]
	v_cndmask_b32_e64 v33, v39, v33, s[38:39]
	v_cndmask_b32_e64 v32, v38, v32, s[38:39]
	v_pk_fma_f32 v[32:33], v[32:33], s[24:25], v[36:37] op_sel_hi:[1,0,1]
	v_pk_fma_f32 v[30:31], v[30:31], s[24:25], v[34:35] op_sel_hi:[1,0,1]
	global_store_dwordx4 v[190:191], v[30:33], off offset:528
	global_load_dwordx4 v[30:33], v[142:143], off offset:528
	s_waitcnt vmcnt(0)
	v_sub_f32_e32 v37, v31, v180
	v_sub_f32_e32 v36, v30, v180
	v_sub_f32_e32 v35, v33, v180
	v_sub_f32_e32 v34, v32, v180
	v_pk_mul_f32 v[36:37], v[182:183], v[36:37]
	v_mov_b32_e32 v183, v182
	v_pk_mul_f32 v[34:35], v[182:183], v[34:35]
	v_pk_fma_f32 v[36:37], v[62:63], v[36:37], v[70:71]
	v_pk_fma_f32 v[34:35], v[64:65], v[34:35], v[72:73]
	v_cndmask_b32_e64 v31, v37, v31, s[38:39]
	v_cndmask_b32_e64 v30, v36, v30, s[38:39]
	v_cndmask_b32_e64 v33, v35, v33, s[38:39]
	v_cndmask_b32_e64 v32, v34, v32, s[38:39]
	v_pk_fma_f32 v[28:29], v[32:33], s[24:25], v[28:29] op_sel_hi:[1,0,1]
	v_pk_fma_f32 v[26:27], v[30:31], s[24:25], v[26:27] op_sel_hi:[1,0,1]
	global_store_dwordx4 v[142:143], v[26:29], off offset:528
	global_load_dwordx4 v[26:29], v[138:139], off offset:528
	s_waitcnt vmcnt(0)
	v_sub_f32_e32 v33, v27, v176
	v_sub_f32_e32 v32, v26, v176
	v_sub_f32_e32 v31, v29, v176
	v_sub_f32_e32 v30, v28, v176
	v_pk_mul_f32 v[32:33], v[178:179], v[32:33]
	v_mov_b32_e32 v179, v178
	v_pk_mul_f32 v[30:31], v[178:179], v[30:31]
	v_pk_fma_f32 v[32:33], v[62:63], v[32:33], v[70:71]
	v_pk_fma_f32 v[30:31], v[64:65], v[30:31], v[72:73]
	v_cndmask_b32_e64 v27, v33, v27, s[38:39]
	v_cndmask_b32_e64 v26, v32, v26, s[38:39]
	v_cndmask_b32_e64 v29, v31, v29, s[38:39]
	v_cndmask_b32_e64 v28, v30, v28, s[38:39]
	v_pk_fma_f32 v[24:25], v[28:29], s[24:25], v[24:25] op_sel_hi:[1,0,1]
	v_pk_fma_f32 v[22:23], v[26:27], s[24:25], v[22:23] op_sel_hi:[1,0,1]
	global_store_dwordx4 v[138:139], v[22:25], off offset:528
	global_load_dwordx4 v[22:25], v[134:135], off offset:528
	s_waitcnt vmcnt(0)
	v_sub_f32_e32 v29, v23, v172
	v_sub_f32_e32 v28, v22, v172
	v_sub_f32_e32 v27, v25, v172
	v_sub_f32_e32 v26, v24, v172
	v_pk_mul_f32 v[28:29], v[174:175], v[28:29]
	v_mov_b32_e32 v175, v174
	v_pk_mul_f32 v[26:27], v[174:175], v[26:27]
	v_pk_fma_f32 v[28:29], v[62:63], v[28:29], v[70:71]
	v_pk_fma_f32 v[26:27], v[64:65], v[26:27], v[72:73]
	v_cndmask_b32_e64 v23, v29, v23, s[38:39]
	v_cndmask_b32_e64 v22, v28, v22, s[38:39]
	v_cndmask_b32_e64 v25, v27, v25, s[38:39]
	v_cndmask_b32_e64 v24, v26, v24, s[38:39]
	v_pk_fma_f32 v[20:21], v[24:25], s[24:25], v[20:21] op_sel_hi:[1,0,1]
	v_pk_fma_f32 v[18:19], v[22:23], s[24:25], v[18:19] op_sel_hi:[1,0,1]
	global_store_dwordx4 v[134:135], v[18:21], off offset:528
	global_load_dwordx4 v[18:21], v[122:123], off offset:528
	s_waitcnt vmcnt(0)
	v_sub_f32_e32 v25, v19, v168
	v_sub_f32_e32 v24, v18, v168
	v_sub_f32_e32 v23, v21, v168
	v_sub_f32_e32 v22, v20, v168
	v_pk_mul_f32 v[24:25], v[170:171], v[24:25]
	v_mov_b32_e32 v171, v170
	v_pk_mul_f32 v[22:23], v[170:171], v[22:23]
	v_pk_fma_f32 v[24:25], v[62:63], v[24:25], v[70:71]
	v_pk_fma_f32 v[22:23], v[64:65], v[22:23], v[72:73]
	v_cndmask_b32_e64 v19, v25, v19, s[38:39]
	v_cndmask_b32_e64 v18, v24, v18, s[38:39]
	v_cndmask_b32_e64 v21, v23, v21, s[38:39]
	v_cndmask_b32_e64 v20, v22, v20, s[38:39]
	v_pk_fma_f32 v[16:17], v[20:21], s[24:25], v[16:17] op_sel_hi:[1,0,1]
	v_pk_fma_f32 v[14:15], v[18:19], s[24:25], v[14:15] op_sel_hi:[1,0,1]
	global_store_dwordx4 v[122:123], v[14:17], off offset:528
	global_load_dwordx4 v[14:17], v[118:119], off offset:528
	s_waitcnt vmcnt(0)
	v_sub_f32_e32 v21, v15, v164
	v_sub_f32_e32 v20, v14, v164
	v_sub_f32_e32 v19, v17, v164
	v_sub_f32_e32 v18, v16, v164
	v_pk_mul_f32 v[20:21], v[166:167], v[20:21]
	v_mov_b32_e32 v167, v166
	v_pk_mul_f32 v[18:19], v[166:167], v[18:19]
	v_pk_fma_f32 v[20:21], v[62:63], v[20:21], v[70:71]
	v_pk_fma_f32 v[18:19], v[64:65], v[18:19], v[72:73]
	v_cndmask_b32_e64 v15, v21, v15, s[38:39]
	v_cndmask_b32_e64 v14, v20, v14, s[38:39]
	v_cndmask_b32_e64 v17, v19, v17, s[38:39]
	v_cndmask_b32_e64 v16, v18, v16, s[38:39]
	v_pk_fma_f32 v[12:13], v[16:17], s[24:25], v[12:13] op_sel_hi:[1,0,1]
	v_pk_fma_f32 v[10:11], v[14:15], s[24:25], v[10:11] op_sel_hi:[1,0,1]
	global_store_dwordx4 v[118:119], v[10:13], off offset:528
	global_load_dwordx4 v[10:13], v[116:117], off offset:528
	s_waitcnt vmcnt(0)
	v_sub_f32_e32 v17, v11, v160
	v_sub_f32_e32 v16, v10, v160
	v_sub_f32_e32 v15, v13, v160
	v_sub_f32_e32 v14, v12, v160
	v_pk_mul_f32 v[16:17], v[162:163], v[16:17]
	v_mov_b32_e32 v163, v162
	v_pk_mul_f32 v[14:15], v[162:163], v[14:15]
	v_pk_fma_f32 v[16:17], v[62:63], v[16:17], v[70:71]
	v_pk_fma_f32 v[14:15], v[64:65], v[14:15], v[72:73]
	v_cndmask_b32_e64 v11, v17, v11, s[38:39]
	v_cndmask_b32_e64 v10, v16, v10, s[38:39]
	v_cndmask_b32_e64 v13, v15, v13, s[38:39]
	v_cndmask_b32_e64 v12, v14, v12, s[38:39]
	v_pk_fma_f32 v[8:9], v[12:13], s[24:25], v[8:9] op_sel_hi:[1,0,1]
	v_pk_fma_f32 v[6:7], v[10:11], s[24:25], v[6:7] op_sel_hi:[1,0,1]
	global_store_dwordx4 v[116:117], v[6:9], off offset:528
	global_load_dwordx4 v[6:9], v[114:115], off offset:528
	s_waitcnt vmcnt(0)
	v_sub_f32_e32 v13, v7, v156
	v_sub_f32_e32 v12, v6, v156
	v_sub_f32_e32 v11, v9, v156
	v_sub_f32_e32 v10, v8, v156
	v_pk_mul_f32 v[12:13], v[158:159], v[12:13]
	v_mov_b32_e32 v159, v158
	v_pk_mul_f32 v[10:11], v[158:159], v[10:11]
	v_pk_fma_f32 v[12:13], v[62:63], v[12:13], v[70:71]
	v_pk_fma_f32 v[10:11], v[64:65], v[10:11], v[72:73]
	v_cndmask_b32_e64 v7, v13, v7, s[38:39]
	v_cndmask_b32_e64 v6, v12, v6, s[38:39]
	v_cndmask_b32_e64 v9, v11, v9, s[38:39]
	v_cndmask_b32_e64 v8, v10, v8, s[38:39]
	v_pk_fma_f32 v[4:5], v[8:9], s[24:25], v[4:5] op_sel_hi:[1,0,1]
	v_pk_fma_f32 v[2:3], v[6:7], s[24:25], v[2:3] op_sel_hi:[1,0,1]
	global_store_dwordx4 v[114:115], v[2:5], off offset:528
	s_cbranch_vccnz .LBB0_871
	s_andn2_b64 vcc, exec, s[0:1]
	s_cbranch_vccnz .LBB0_870
	s_barrier
	s_branch .LBB0_870
